# adds sc1 (write-through) on the SwiGLU epilogue stores of ACT so the grid barrier's L2 writeback has less dirty data
# baseline (speedup 1.0000x reference)
.LBB0_417:
	s_andn2_b64 vcc, exec, s[6:7]
	s_cbranch_vccnz .LBB0_419
	v_mul_f32_e32 v202, 0xbfb8aa3b, v178
	v_mul_f32_e32 v203, 0xbfb8aa3b, v179
	v_exp_f32_e32 v202, v202
	v_exp_f32_e32 v203, v203
	v_pk_mul_f32 v[194:195], v[126:127], v[176:177] op_sel_hi:[1,0]
	v_pk_mul_f32 v[198:199], v[118:119], v[176:177] op_sel_hi:[1,0]
	v_add_f32_e32 v202, 1.0, v202
	v_add_f32_e32 v203, 1.0, v203
	v_rcp_f32_e32 v202, v202
	v_rcp_f32_e32 v203, v203
	v_pk_mul_f32 v[196:197], v[122:123], v[176:177] op_sel_hi:[1,0]
	v_pk_mul_f32 v[200:201], v[114:115], v[176:177] op_sel_hi:[1,0]
	s_lshl_b32 s0, s10, 7
	v_pk_mul_f32 v[178:179], v[178:179], v[202:203]
	s_ashr_i32 s1, s0, 31
	v_pk_mul_f32 v[178:179], v[180:181], v[178:179]
	s_lshl_b64 s[0:1], s[0:1], 1
	v_cvt_pk_bf16_f32 v178, v178, v179
	v_mul_f32_e32 v179, 0xbfb8aa3b, v194
	v_exp_f32_e32 v179, v179
	s_nop 0
	v_add_f32_e32 v179, 1.0, v179
	v_rcp_f32_e32 v180, v179
	v_mul_f32_e32 v179, 0xbfb8aa3b, v195
	v_exp_f32_e32 v179, v179
	s_nop 0
	v_add_f32_e32 v179, 1.0, v179
	v_rcp_f32_e32 v181, v179
	s_nop 0
	v_pk_mul_f32 v[180:181], v[194:195], v[180:181]
	s_nop 0
	v_pk_mul_f32 v[180:181], v[198:199], v[180:181]
	s_nop 0
	v_cvt_pk_bf16_f32 v179, v180, v181
	v_mul_f32_e32 v180, 0xbfb8aa3b, v136
	v_mul_f32_e32 v181, 0xbfb8aa3b, v137
	v_exp_f32_e32 v180, v180
	v_exp_f32_e32 v181, v181
	v_add_f32_e32 v180, 1.0, v180
	v_add_f32_e32 v181, 1.0, v181
	v_rcp_f32_e32 v180, v180
	v_rcp_f32_e32 v181, v181
	s_nop 0
	v_pk_mul_f32 v[136:137], v[136:137], v[180:181]
	s_nop 0
	v_pk_mul_f32 v[136:137], v[138:139], v[136:137]
	v_pk_mul_f32 v[138:139], v[106:107], v[176:177] op_sel:[0,1]
	v_cvt_pk_bf16_f32 v180, v136, v137
	v_mul_f32_e32 v136, 0xbfb8aa3b, v196
	v_mul_f32_e32 v137, 0xbfb8aa3b, v197
	v_exp_f32_e32 v136, v136
	v_exp_f32_e32 v137, v137
	v_add_f32_e32 v136, 1.0, v136
	v_add_f32_e32 v137, 1.0, v137
	v_rcp_f32_e32 v136, v136
	v_rcp_f32_e32 v137, v137
	s_nop 0
	v_pk_mul_f32 v[136:137], v[196:197], v[136:137]
	s_nop 0
	v_pk_mul_f32 v[136:137], v[200:201], v[136:137]
	s_nop 0
	v_cvt_pk_bf16_f32 v181, v136, v137
	v_mad_u64_u32 v[136:137], s[2:3], s52, v168, 0
	v_mul_f32_e32 v168, 0xbfb8aa3b, v132
	v_exp_f32_e32 v168, v168
	v_add3_u32 v137, v137, v187, v193
	v_lshl_add_u64 v[136:137], v[136:137], 1, s[4:5]
	v_lshl_add_u64 v[136:137], v[136:137], 0, s[0:1]
	v_lshl_add_u64 v[136:137], v[136:137], 0, v[144:145]
	v_add_f32_e32 v168, 1.0, v168
	global_store_dwordx4 v[136:137], v[178:181], off sc1
	v_pk_mul_f32 v[136:137], v[110:111], v[176:177] op_sel:[0,1]
	s_nop 0
	v_rcp_f32_e32 v180, v168
	v_mul_f32_e32 v168, 0xbfb8aa3b, v133
	v_exp_f32_e32 v168, v168
	v_pk_mul_f32 v[178:179], v[102:103], v[176:177] op_sel:[0,1]
	v_pk_mul_f32 v[176:177], v[98:99], v[176:177] op_sel:[0,1]
	v_add_f32_e32 v168, 1.0, v168
	v_rcp_f32_e32 v181, v168
	s_nop 0
	v_pk_mul_f32 v[132:133], v[132:133], v[180:181]
	s_nop 0
	v_pk_mul_f32 v[132:133], v[134:135], v[132:133]
	s_nop 0
	v_cvt_pk_bf16_f32 v132, v132, v133
	v_mul_f32_e32 v133, 0xbfb8aa3b, v136
	v_exp_f32_e32 v133, v133
	s_nop 0
	v_add_f32_e32 v133, 1.0, v133
	v_rcp_f32_e32 v134, v133
	v_mul_f32_e32 v133, 0xbfb8aa3b, v137
	v_exp_f32_e32 v133, v133
	s_nop 0
	v_add_f32_e32 v133, 1.0, v133
	v_rcp_f32_e32 v135, v133
	s_nop 0
	v_pk_mul_f32 v[134:135], v[136:137], v[134:135]
	s_nop 0
	v_pk_mul_f32 v[134:135], v[178:179], v[134:135]
	v_pk_mul_f32 v[136:137], v[86:87], v[172:173] op_sel_hi:[1,0]
	v_cvt_pk_bf16_f32 v133, v134, v135
	v_mul_f32_e32 v134, 0xbfb8aa3b, v128
	v_mul_f32_e32 v135, 0xbfb8aa3b, v129
	v_exp_f32_e32 v134, v134
	v_exp_f32_e32 v135, v135
	v_pk_mul_f32 v[178:179], v[80:81], v[172:173] op_sel_hi:[1,0]
	v_add_f32_e32 v134, 1.0, v134
	v_add_f32_e32 v135, 1.0, v135
	v_rcp_f32_e32 v134, v134
	v_rcp_f32_e32 v135, v135
	s_nop 0
	v_pk_mul_f32 v[128:129], v[128:129], v[134:135]
	s_nop 0
	v_pk_mul_f32 v[128:129], v[130:131], v[128:129]
	v_pk_mul_f32 v[130:131], v[94:95], v[172:173] op_sel_hi:[1,0]
	v_cvt_pk_bf16_f32 v134, v128, v129
	v_mul_f32_e32 v128, 0xbfb8aa3b, v138
	v_mul_f32_e32 v129, 0xbfb8aa3b, v139
	v_exp_f32_e32 v128, v128
	v_exp_f32_e32 v129, v129
	v_add_f32_e32 v128, 1.0, v128
	v_add_f32_e32 v129, 1.0, v129
	v_rcp_f32_e32 v128, v128
	v_rcp_f32_e32 v129, v129
	s_nop 0
	v_pk_mul_f32 v[128:129], v[138:139], v[128:129]
	s_nop 0
	v_pk_mul_f32 v[128:129], v[176:177], v[128:129]
	v_pk_mul_f32 v[138:139], v[84:85], v[172:173] op_sel_hi:[1,0]
	v_cvt_pk_bf16_f32 v135, v128, v129
	v_mad_u64_u32 v[128:129], s[2:3], s52, v191, 0
	v_add3_u32 v129, v129, v187, v192
	v_lshl_add_u64 v[128:129], v[128:129], 1, s[4:5]
	v_lshl_add_u64 v[128:129], v[128:129], 0, s[0:1]
	v_lshl_add_u64 v[128:129], v[128:129], 0, v[144:145]
	global_store_dwordx4 v[128:129], v[132:135], off sc1
	v_pk_mul_f32 v[128:129], v[92:93], v[172:173] op_sel_hi:[1,0]
	v_pk_mul_f32 v[176:177], v[82:83], v[172:173] op_sel_hi:[1,0]
	v_mul_f32_e32 v168, 0xbfb8aa3b, v128
	v_exp_f32_e32 v168, v168
	v_pk_mul_f32 v[134:135], v[88:89], v[172:173] op_sel_hi:[1,0]
	v_pk_mul_f32 v[132:133], v[90:91], v[172:173] op_sel_hi:[1,0]
	v_add_f32_e32 v168, 1.0, v168
	v_rcp_f32_e32 v180, v168
	v_mul_f32_e32 v168, 0xbfb8aa3b, v129
	v_exp_f32_e32 v168, v168
	s_nop 0
	v_add_f32_e32 v168, 1.0, v168
	v_rcp_f32_e32 v181, v168
	s_nop 0
	v_pk_mul_f32 v[128:129], v[128:129], v[180:181]
	s_nop 0
	v_pk_mul_f32 v[128:129], v[138:139], v[128:129]
	s_nop 0
	v_cvt_pk_bf16_f32 v128, v128, v129
	v_mul_f32_e32 v129, 0xbfb8aa3b, v130
	v_exp_f32_e32 v129, v129
	s_nop 0
	v_add_f32_e32 v129, 1.0, v129
	v_rcp_f32_e32 v138, v129
	v_mul_f32_e32 v129, 0xbfb8aa3b, v131
	v_exp_f32_e32 v129, v129
	s_nop 0
	v_add_f32_e32 v129, 1.0, v129
	v_rcp_f32_e32 v139, v129
	s_nop 0
	v_pk_mul_f32 v[130:131], v[130:131], v[138:139]
	s_nop 0
	v_pk_mul_f32 v[130:131], v[136:137], v[130:131]
	v_pk_mul_f32 v[136:137], v[70:71], v[166:167] op_sel_hi:[1,0]
	v_cvt_pk_bf16_f32 v129, v130, v131
	v_mul_f32_e32 v130, 0xbfb8aa3b, v134
	v_mul_f32_e32 v131, 0xbfb8aa3b, v135
	v_exp_f32_e32 v130, v130
	v_exp_f32_e32 v131, v131
	v_pk_mul_f32 v[138:139], v[68:69], v[166:167] op_sel_hi:[1,0]
	v_add_f32_e32 v130, 1.0, v130
	v_add_f32_e32 v131, 1.0, v131
	v_rcp_f32_e32 v130, v130
	v_rcp_f32_e32 v131, v131
	s_nop 0
	v_pk_mul_f32 v[130:131], v[134:135], v[130:131]
	s_nop 0
	v_pk_mul_f32 v[130:131], v[178:179], v[130:131]
	v_pk_mul_f32 v[178:179], v[64:65], v[166:167] op_sel_hi:[1,0]
	v_cvt_pk_bf16_f32 v130, v130, v131
	v_mul_f32_e32 v131, 0xbfb8aa3b, v132
	v_exp_f32_e32 v131, v131
	s_nop 0
	v_add_f32_e32 v131, 1.0, v131
	v_rcp_f32_e32 v134, v131
	v_mul_f32_e32 v131, 0xbfb8aa3b, v133
	v_exp_f32_e32 v131, v131
	s_nop 0
	v_add_f32_e32 v131, 1.0, v131
	v_rcp_f32_e32 v135, v131
	s_nop 0
	v_pk_mul_f32 v[132:133], v[132:133], v[134:135]
	s_nop 0
	v_pk_mul_f32 v[132:133], v[176:177], v[132:133]
	v_pk_mul_f32 v[134:135], v[72:73], v[166:167] op_sel_hi:[1,0]
	v_cvt_pk_bf16_f32 v131, v132, v133
	v_mad_u64_u32 v[132:133], s[2:3], s52, v189, 0
	v_add3_u32 v133, v133, v187, v190
	v_lshl_add_u64 v[132:133], v[132:133], 1, s[4:5]
	v_lshl_add_u64 v[132:133], v[132:133], 0, s[0:1]
	v_lshl_add_u64 v[132:133], v[132:133], 0, v[144:145]
	global_store_dwordx4 v[132:133], v[128:131], off sc1
	v_pk_mul_f32 v[132:133], v[74:75], v[166:167] op_sel_hi:[1,0]
	v_pk_mul_f32 v[176:177], v[66:67], v[166:167] op_sel_hi:[1,0]
	v_pk_mul_f32 v[128:129], v[76:77], v[166:167] op_sel_hi:[1,0]
	v_pk_mul_f32 v[130:131], v[78:79], v[166:167] op_sel_hi:[1,0]
	v_mul_f32_e32 v166, 0xbfb8aa3b, v128
	v_exp_f32_e32 v166, v166
	s_nop 0
	v_add_f32_e32 v166, 1.0, v166
	v_rcp_f32_e32 v180, v166
	v_mul_f32_e32 v166, 0xbfb8aa3b, v129
	v_exp_f32_e32 v166, v166
	s_nop 0
	v_add_f32_e32 v166, 1.0, v166
	v_rcp_f32_e32 v181, v166
	s_nop 0
	v_pk_mul_f32 v[128:129], v[128:129], v[180:181]
	s_nop 0
	v_pk_mul_f32 v[128:129], v[138:139], v[128:129]
	s_nop 0
	v_cvt_pk_bf16_f32 v128, v128, v129
	v_mul_f32_e32 v129, 0xbfb8aa3b, v130
	v_exp_f32_e32 v129, v129
	s_nop 0
	v_add_f32_e32 v129, 1.0, v129
	v_rcp_f32_e32 v138, v129
	v_mul_f32_e32 v129, 0xbfb8aa3b, v131
	v_exp_f32_e32 v129, v129
	s_nop 0
	v_add_f32_e32 v129, 1.0, v129
	v_rcp_f32_e32 v139, v129
	s_nop 0
	v_pk_mul_f32 v[130:131], v[130:131], v[138:139]
	s_nop 0
	v_pk_mul_f32 v[130:131], v[136:137], v[130:131]
	v_pk_mul_f32 v[138:139], v[52:53], v[174:175] op_sel_hi:[1,0]
	v_cvt_pk_bf16_f32 v129, v130, v131
	v_mul_f32_e32 v130, 0xbfb8aa3b, v134
	v_mul_f32_e32 v131, 0xbfb8aa3b, v135
	v_exp_f32_e32 v130, v130
	v_exp_f32_e32 v131, v131
	v_pk_mul_f32 v[136:137], v[54:55], v[174:175] op_sel_hi:[1,0]
	v_add_f32_e32 v130, 1.0, v130
	v_add_f32_e32 v131, 1.0, v131
	v_rcp_f32_e32 v130, v130
	v_rcp_f32_e32 v131, v131
	s_nop 0
	v_pk_mul_f32 v[130:131], v[134:135], v[130:131]
	s_nop 0
	v_pk_mul_f32 v[130:131], v[178:179], v[130:131]
	v_pk_mul_f32 v[178:179], v[48:49], v[174:175] op_sel_hi:[1,0]
	v_cvt_pk_bf16_f32 v130, v130, v131
	v_mul_f32_e32 v131, 0xbfb8aa3b, v132
	v_exp_f32_e32 v131, v131
	s_nop 0
	v_add_f32_e32 v131, 1.0, v131
	v_rcp_f32_e32 v134, v131
	v_mul_f32_e32 v131, 0xbfb8aa3b, v133
	v_exp_f32_e32 v131, v131
	s_nop 0
	v_add_f32_e32 v131, 1.0, v131
	v_rcp_f32_e32 v135, v131
	s_nop 0
	v_pk_mul_f32 v[132:133], v[132:133], v[134:135]
	s_nop 0
	v_pk_mul_f32 v[132:133], v[176:177], v[132:133]
	v_pk_mul_f32 v[134:135], v[56:57], v[174:175] op_sel_hi:[1,0]
	v_cvt_pk_bf16_f32 v131, v132, v133
	v_mad_u64_u32 v[132:133], s[2:3], s52, v186, 0
	v_add3_u32 v133, v133, v187, v188
	v_lshl_add_u64 v[132:133], v[132:133], 1, s[4:5]
	v_lshl_add_u64 v[132:133], v[132:133], 0, s[0:1]
	v_lshl_add_u64 v[132:133], v[132:133], 0, v[144:145]
	global_store_dwordx4 v[132:133], v[128:131], off sc1
	v_pk_mul_f32 v[132:133], v[58:59], v[174:175] op_sel_hi:[1,0]
	v_pk_mul_f32 v[176:177], v[50:51], v[174:175] op_sel_hi:[1,0]
	v_pk_mul_f32 v[128:129], v[60:61], v[174:175] op_sel_hi:[1,0]
	v_pk_mul_f32 v[130:131], v[62:63], v[174:175] op_sel_hi:[1,0]
	v_mul_f32_e32 v166, 0xbfb8aa3b, v128
	v_exp_f32_e32 v166, v166
	s_nop 0
	v_add_f32_e32 v166, 1.0, v166
	v_rcp_f32_e32 v180, v166
	v_mul_f32_e32 v166, 0xbfb8aa3b, v129
	v_exp_f32_e32 v166, v166
	s_nop 0
	v_add_f32_e32 v166, 1.0, v166
	v_rcp_f32_e32 v181, v166
	s_nop 0
	v_pk_mul_f32 v[128:129], v[128:129], v[180:181]
	s_nop 0
	v_pk_mul_f32 v[128:129], v[138:139], v[128:129]
	s_nop 0
	v_cvt_pk_bf16_f32 v128, v128, v129
	v_mul_f32_e32 v129, 0xbfb8aa3b, v130
	v_exp_f32_e32 v129, v129
	s_nop 0
	v_add_f32_e32 v129, 1.0, v129
	v_rcp_f32_e32 v138, v129
	v_mul_f32_e32 v129, 0xbfb8aa3b, v131
	v_exp_f32_e32 v129, v129
	s_nop 0
	v_add_f32_e32 v129, 1.0, v129
	v_rcp_f32_e32 v139, v129
	s_nop 0
	v_pk_mul_f32 v[130:131], v[130:131], v[138:139]
	s_nop 0
	v_pk_mul_f32 v[130:131], v[136:137], v[130:131]
	v_pk_mul_f32 v[136:137], v[38:39], v[142:143] op_sel_hi:[1,0]
	v_cvt_pk_bf16_f32 v129, v130, v131
	v_mul_f32_e32 v130, 0xbfb8aa3b, v134
	v_mul_f32_e32 v131, 0xbfb8aa3b, v135
	v_exp_f32_e32 v130, v130
	v_exp_f32_e32 v131, v131
	v_pk_mul_f32 v[138:139], v[36:37], v[142:143] op_sel_hi:[1,0]
	v_add_f32_e32 v130, 1.0, v130
	v_add_f32_e32 v131, 1.0, v131
	v_rcp_f32_e32 v130, v130
	v_rcp_f32_e32 v131, v131
	s_nop 0
	v_pk_mul_f32 v[130:131], v[134:135], v[130:131]
	s_nop 0
	v_pk_mul_f32 v[130:131], v[178:179], v[130:131]
	v_pk_mul_f32 v[178:179], v[32:33], v[142:143] op_sel_hi:[1,0]
	v_cvt_pk_bf16_f32 v130, v130, v131
	v_mul_f32_e32 v131, 0xbfb8aa3b, v132
	v_exp_f32_e32 v131, v131
	s_nop 0
	v_add_f32_e32 v131, 1.0, v131
	v_rcp_f32_e32 v134, v131
	v_mul_f32_e32 v131, 0xbfb8aa3b, v133
	v_exp_f32_e32 v131, v131
	s_nop 0
	v_add_f32_e32 v131, 1.0, v131
	v_rcp_f32_e32 v135, v131
	s_nop 0
	v_pk_mul_f32 v[132:133], v[132:133], v[134:135]
	s_nop 0
	v_pk_mul_f32 v[132:133], v[176:177], v[132:133]
	v_mul_lo_u32 v134, s52, v185
	v_cvt_pk_bf16_f32 v131, v132, v133
	v_mad_u64_u32 v[132:133], s[2:3], s52, v183, 0
	v_add3_u32 v133, v133, v134, v184
	v_lshl_add_u64 v[132:133], v[132:133], 1, s[4:5]
	v_lshl_add_u64 v[132:133], v[132:133], 0, s[0:1]
	v_lshl_add_u64 v[132:133], v[132:133], 0, v[144:145]
	global_store_dwordx4 v[132:133], v[128:131], off sc1
	v_pk_mul_f32 v[132:133], v[42:43], v[142:143] op_sel_hi:[1,0]
	v_pk_mul_f32 v[134:135], v[40:41], v[142:143] op_sel_hi:[1,0]
	v_pk_mul_f32 v[128:129], v[44:45], v[142:143] op_sel_hi:[1,0]
	v_pk_mul_f32 v[130:131], v[46:47], v[142:143] op_sel_hi:[1,0]
	v_pk_mul_f32 v[176:177], v[34:35], v[142:143] op_sel_hi:[1,0]
	v_mul_f32_e32 v142, 0xbfb8aa3b, v128
	v_exp_f32_e32 v142, v142
	s_nop 0
	v_add_f32_e32 v142, 1.0, v142
	v_rcp_f32_e32 v180, v142
	v_mul_f32_e32 v142, 0xbfb8aa3b, v129
	v_exp_f32_e32 v142, v142
	s_nop 0
	v_add_f32_e32 v142, 1.0, v142
	v_rcp_f32_e32 v181, v142
	s_nop 0
	v_pk_mul_f32 v[128:129], v[128:129], v[180:181]
	s_nop 0
	v_pk_mul_f32 v[128:129], v[138:139], v[128:129]
	s_nop 0
	v_cvt_pk_bf16_f32 v128, v128, v129
	v_mul_f32_e32 v129, 0xbfb8aa3b, v130
	v_exp_f32_e32 v129, v129
	s_nop 0
	v_add_f32_e32 v129, 1.0, v129
	v_rcp_f32_e32 v138, v129
	v_mul_f32_e32 v129, 0xbfb8aa3b, v131
	v_exp_f32_e32 v129, v129
	s_nop 0
	v_add_f32_e32 v129, 1.0, v129
	v_rcp_f32_e32 v139, v129
	s_nop 0
	v_pk_mul_f32 v[130:131], v[130:131], v[138:139]
	s_nop 0
	v_pk_mul_f32 v[130:131], v[136:137], v[130:131]
	v_pk_mul_f32 v[138:139], v[20:21], v[170:171] op_sel_hi:[1,0]
	v_cvt_pk_bf16_f32 v129, v130, v131
	v_mul_f32_e32 v130, 0xbfb8aa3b, v134
	v_mul_f32_e32 v131, 0xbfb8aa3b, v135
	v_exp_f32_e32 v130, v130
	v_exp_f32_e32 v131, v131
	v_pk_mul_f32 v[136:137], v[22:23], v[170:171] op_sel_hi:[1,0]
	v_add_f32_e32 v130, 1.0, v130
	v_add_f32_e32 v131, 1.0, v131
	v_rcp_f32_e32 v130, v130
	v_rcp_f32_e32 v131, v131
	s_nop 0
	v_pk_mul_f32 v[130:131], v[134:135], v[130:131]
	s_nop 0
	v_pk_mul_f32 v[130:131], v[178:179], v[130:131]
	s_nop 0
	v_cvt_pk_bf16_f32 v130, v130, v131
	v_mul_f32_e32 v131, 0xbfb8aa3b, v132
	v_exp_f32_e32 v131, v131
	s_nop 0
	v_add_f32_e32 v131, 1.0, v131
	v_rcp_f32_e32 v134, v131
	v_mul_f32_e32 v131, 0xbfb8aa3b, v133
	v_exp_f32_e32 v131, v131
	s_nop 0
	v_add_f32_e32 v131, 1.0, v131
	v_rcp_f32_e32 v135, v131
	s_nop 0
	v_pk_mul_f32 v[132:133], v[132:133], v[134:135]
	s_nop 0
	v_pk_mul_f32 v[132:133], v[176:177], v[132:133]
	v_mul_lo_u32 v134, s52, v182
	v_cvt_pk_bf16_f32 v131, v132, v133
	v_mad_u64_u32 v[132:133], s[2:3], s52, v169, 0
	v_add3_u32 v133, v133, v134, v171
	v_lshl_add_u64 v[132:133], v[132:133], 1, s[4:5]
	v_lshl_add_u64 v[132:133], v[132:133], 0, s[0:1]
	v_lshl_add_u64 v[132:133], v[132:133], 0, v[144:145]
	global_store_dwordx4 v[132:133], v[128:131], off sc1
	v_pk_mul_f32 v[134:135], v[24:25], v[170:171] op_sel_hi:[1,0]
	v_pk_mul_f32 v[132:133], v[26:27], v[170:171] op_sel_hi:[1,0]
	v_pk_mul_f32 v[128:129], v[28:29], v[170:171] op_sel_hi:[1,0]
	v_pk_mul_f32 v[130:131], v[30:31], v[170:171] op_sel_hi:[1,0]
	v_mul_f32_e32 v142, 0xbfb8aa3b, v128
	v_exp_f32_e32 v142, v142
	v_pk_mul_f32 v[168:169], v[18:19], v[170:171] op_sel_hi:[1,0]
	v_pk_mul_f32 v[170:171], v[16:17], v[170:171] op_sel_hi:[1,0]
	v_add_f32_e32 v142, 1.0, v142
	v_rcp_f32_e32 v176, v142
	v_mul_f32_e32 v142, 0xbfb8aa3b, v129
	v_exp_f32_e32 v142, v142
	s_nop 0
	v_add_f32_e32 v142, 1.0, v142
	v_rcp_f32_e32 v177, v142
	s_nop 0
	v_pk_mul_f32 v[128:129], v[128:129], v[176:177]
	s_nop 0
	v_pk_mul_f32 v[128:129], v[138:139], v[128:129]
	s_nop 0
	v_cvt_pk_bf16_f32 v128, v128, v129
	v_mul_f32_e32 v129, 0xbfb8aa3b, v130
	v_exp_f32_e32 v129, v129
	s_nop 0
	v_add_f32_e32 v129, 1.0, v129
	v_rcp_f32_e32 v138, v129
	v_mul_f32_e32 v129, 0xbfb8aa3b, v131
	v_exp_f32_e32 v129, v129
	s_nop 0
	v_add_f32_e32 v129, 1.0, v129
	v_rcp_f32_e32 v139, v129
	s_nop 0
	v_pk_mul_f32 v[130:131], v[130:131], v[138:139]
	s_nop 0
	v_pk_mul_f32 v[130:131], v[136:137], v[130:131]
	v_pk_mul_f32 v[136:137], v[6:7], v[140:141] op_sel_hi:[1,0]
	v_cvt_pk_bf16_f32 v129, v130, v131
	v_mul_f32_e32 v130, 0xbfb8aa3b, v134
	v_mul_f32_e32 v131, 0xbfb8aa3b, v135
	v_exp_f32_e32 v130, v130
	v_exp_f32_e32 v131, v131
	v_pk_mul_f32 v[138:139], v[4:5], v[140:141] op_sel_hi:[1,0]
	v_add_f32_e32 v130, 1.0, v130
	v_add_f32_e32 v131, 1.0, v131
	v_rcp_f32_e32 v130, v130
	v_rcp_f32_e32 v131, v131
	s_nop 0
	v_pk_mul_f32 v[130:131], v[134:135], v[130:131]
	s_nop 0
	v_pk_mul_f32 v[130:131], v[170:171], v[130:131]
	s_nop 0
	v_cvt_pk_bf16_f32 v130, v130, v131
	v_mul_f32_e32 v131, 0xbfb8aa3b, v132
	v_exp_f32_e32 v131, v131
	s_nop 0
	v_add_f32_e32 v131, 1.0, v131
	v_rcp_f32_e32 v134, v131
	v_mul_f32_e32 v131, 0xbfb8aa3b, v133
	v_exp_f32_e32 v131, v131
	s_nop 0
	v_add_f32_e32 v131, 1.0, v131
	v_rcp_f32_e32 v135, v131
	s_nop 0
	v_pk_mul_f32 v[132:133], v[132:133], v[134:135]
	s_nop 0
	v_pk_mul_f32 v[132:133], v[168:169], v[132:133]
	v_mul_lo_u32 v134, s52, v167
	v_cvt_pk_bf16_f32 v131, v132, v133
	v_mad_u64_u32 v[132:133], s[2:3], s52, v143, 0
	v_add3_u32 v133, v133, v134, v165
	v_lshl_add_u64 v[132:133], v[132:133], 1, s[4:5]
	v_lshl_add_u64 v[132:133], v[132:133], 0, s[0:1]
	v_lshl_add_u64 v[132:133], v[132:133], 0, v[144:145]
	global_store_dwordx4 v[132:133], v[128:131], off sc1
	v_pk_mul_f32 v[132:133], v[10:11], v[140:141] op_sel_hi:[1,0]
	v_pk_mul_f32 v[134:135], v[8:9], v[140:141] op_sel_hi:[1,0]
	v_pk_mul_f32 v[128:129], v[12:13], v[140:141] op_sel_hi:[1,0]
	v_pk_mul_f32 v[130:131], v[14:15], v[140:141] op_sel_hi:[1,0]
	v_pk_mul_f32 v[142:143], v[2:3], v[140:141] op_sel_hi:[1,0]
	v_pk_mul_f32 v[166:167], v[0:1], v[140:141] op_sel_hi:[1,0]
	v_mul_f32_e32 v140, 0xbfb8aa3b, v128
	v_exp_f32_e32 v140, v140
	s_nop 0
	v_add_f32_e32 v140, 1.0, v140
	v_rcp_f32_e32 v168, v140
	v_mul_f32_e32 v140, 0xbfb8aa3b, v129
	v_exp_f32_e32 v140, v140
	s_nop 0
	v_add_f32_e32 v140, 1.0, v140
	v_rcp_f32_e32 v169, v140
	s_nop 0
	v_pk_mul_f32 v[128:129], v[128:129], v[168:169]
	s_nop 0
	v_pk_mul_f32 v[128:129], v[138:139], v[128:129]
	s_nop 0
	v_cvt_pk_bf16_f32 v128, v128, v129
	v_mul_f32_e32 v129, 0xbfb8aa3b, v130
	v_exp_f32_e32 v129, v129
	s_nop 0
	v_add_f32_e32 v129, 1.0, v129
	v_rcp_f32_e32 v138, v129
	v_mul_f32_e32 v129, 0xbfb8aa3b, v131
	v_exp_f32_e32 v129, v129
	s_nop 0
	v_add_f32_e32 v129, 1.0, v129
	v_rcp_f32_e32 v139, v129
	s_nop 0
	v_pk_mul_f32 v[130:131], v[130:131], v[138:139]
	s_nop 0
	v_pk_mul_f32 v[130:131], v[136:137], v[130:131]
	s_nop 0
	v_cvt_pk_bf16_f32 v129, v130, v131
	v_mul_f32_e32 v130, 0xbfb8aa3b, v134
	v_mul_f32_e32 v131, 0xbfb8aa3b, v135
	v_exp_f32_e32 v130, v130
	v_exp_f32_e32 v131, v131
	v_add_f32_e32 v130, 1.0, v130
	v_add_f32_e32 v131, 1.0, v131
	v_rcp_f32_e32 v130, v130
	v_rcp_f32_e32 v131, v131
	s_nop 0
	v_pk_mul_f32 v[130:131], v[134:135], v[130:131]
	s_nop 0
	v_pk_mul_f32 v[130:131], v[166:167], v[130:131]
	s_nop 0
	v_cvt_pk_bf16_f32 v130, v130, v131
	v_mul_f32_e32 v131, 0xbfb8aa3b, v132
	v_exp_f32_e32 v131, v131
	s_nop 0
	v_add_f32_e32 v131, 1.0, v131
	v_rcp_f32_e32 v134, v131
	v_mul_f32_e32 v131, 0xbfb8aa3b, v133
	v_exp_f32_e32 v131, v131
	s_nop 0
	v_add_f32_e32 v131, 1.0, v131
	v_rcp_f32_e32 v135, v131
	s_nop 0
	v_pk_mul_f32 v[132:133], v[132:133], v[134:135]
	s_nop 0
	v_pk_mul_f32 v[132:133], v[142:143], v[132:133]
	v_mul_lo_u32 v135, s53, v141
	v_cvt_pk_bf16_f32 v131, v132, v133
	v_ashrrev_i32_e32 v132, 31, v141
	v_mul_lo_u32 v134, s52, v132
	v_mad_u64_u32 v[132:133], s[2:3], s52, v141, 0
	v_add3_u32 v133, v133, v134, v135
	v_lshl_add_u64 v[132:133], v[132:133], 1, s[4:5]
	v_lshl_add_u64 v[132:133], v[132:133], 0, s[0:1]
	v_lshl_add_u64 v[132:133], v[132:133], 0, v[144:145]
	global_store_dwordx4 v[132:133], v[128:131], off sc1
